# attention phase B: raise wave priority for the compute core of a step (between the tile writes and the next register-stage loads)
# speedup vs baseline: 1.0087x; 1.0044x over previous
.LBB0_546:
	s_cmp_eq_u32 s77, 1
	s_cselect_b32 s0, 2, 4
	s_lshr_b32 s1, 16, s0
	s_lshl_b32 s18, s67, 6
	s_waitcnt vmcnt(14) lgkmcnt(2)
	ds_write_b128 v219, v[12:15]
	s_waitcnt vmcnt(12)
	ds_write_b128 v219, v[24:27] offset:1152
	s_waitcnt vmcnt(10)
	ds_write_b128 v219, v[32:35] offset:2304
	s_waitcnt vmcnt(8)
	ds_write_b128 v219, v[40:43] offset:3456
	s_waitcnt vmcnt(6)
	ds_write_b128 v219, v[52:55] offset:4608
	s_waitcnt vmcnt(4)
	ds_write_b128 v219, v[64:67] offset:5760
	s_waitcnt vmcnt(2)
	ds_write_b128 v219, v[76:79] offset:6912
	s_waitcnt vmcnt(0)
	ds_write_b128 v219, v[88:91] offset:8064
	s_waitcnt lgkmcnt(8)
	ds_write_b128 v220, v[4:7] offset:9216
	ds_write_b128 v220, v[8:11] offset:10240
	ds_write_b128 v220, v[16:19] offset:11264
	ds_write_b128 v220, v[20:23] offset:12288
	ds_write_b128 v220, v[28:31] offset:13312
	ds_write_b128 v220, v[36:39] offset:14336
	ds_write_b128 v220, v[44:47] offset:15360
	ds_write_b128 v220, v[68:71] offset:16384
	s_setprio 1
	v_mul_u32_u24_e32 v2, s1, v173
	s_sub_i32 s16, 0x80, s18
	s_lshr_b32 s0, s8, s0
	v_mov_b32_e32 v3, s16
	s_sub_i32 s19, s16, s0
	v_subrev_u32_e32 v2, s18, v2
	v_add_u32_e32 v228, v207, v192
	v_add_u32_e32 v230, v207, v194
	v_mad_u32_u24 v18, s1, v173, v3
	s_cmp_lg_u32 s77, 2
	v_max_i32_e32 v19, s19, v2
	v_add_u32_e32 v229, v207, v193
	ds_read_b128 v[10:13], v228 offset:9216
	ds_read_b128 v[14:17], v229 offset:9216
	v_add_u32_e32 v231, v207, v195
	ds_read_b128 v[6:9], v230 offset:9728
	ds_read_b128 v[2:5], v231 offset:9728
	s_cselect_b64 s[0:1], -1, 0
	s_cmp_lg_u32 s67, 2
	s_cselect_b64 s[16:17], -1, 0
	s_or_b64 s[0:1], s[16:17], s[0:1]
	v_sub_u32_e32 v18, v18, v19
	v_sub_u32_e32 v25, v176, v19
	s_mov_b64 s[16:17], -1
	s_and_b64 vcc, exec, s[0:1]
	v_add_u32_e32 v225, s45, v175
	v_cmp_le_u32_e64 s[0:1], v25, v18
	v_add_u32_e32 v26, 1, v25
	v_add_u32_e32 v24, 2, v25
	v_add_u32_e32 v23, 3, v25
	v_add_u32_e32 v22, 4, v25
	v_add_u32_e32 v21, 5, v25
	v_add_u32_e32 v20, 6, v25
	v_add_u32_e32 v19, 7, v25
	s_cbranch_vccz .LBB0_548
	s_waitcnt vmcnt(1) lgkmcnt(3)
	v_mfma_f32_16x16x32_bf16 v[28:31], v[10:13], v[132:135], 0
	ds_read_b128 v[32:35], v228 offset:13312
	ds_read_b128 v[36:39], v229 offset:13312
	v_cmp_le_u32_e32 vcc, v26, v18
	ds_read_b128 v[40:43], v230 offset:13824
	ds_read_b128 v[44:47], v231 offset:13824
	s_waitcnt vmcnt(0) lgkmcnt(6)
	v_mfma_f32_16x16x32_bf16 v[28:31], v[14:17], v[136:139], v[28:31]
	s_mov_b64 s[16:17], 0
	s_waitcnt lgkmcnt(5)
	v_mfma_f32_16x16x32_bf16 v[52:55], v[6:9], v[132:135], 0
	s_waitcnt lgkmcnt(4)
	v_mfma_f32_16x16x32_bf16 v[52:55], v[2:5], v[136:139], v[52:55]
	s_nop 2
	v_cndmask_b32_e32 v64, v217, v29, vcc
	v_cmp_le_u32_e32 vcc, v24, v18
	v_cndmask_b32_e64 v27, v217, v28, s[0:1]
	s_nop 0
	v_cndmask_b32_e32 v65, v217, v30, vcc
	v_cmp_le_u32_e32 vcc, v23, v18
	s_nop 1
	v_cndmask_b32_e32 v66, v217, v31, vcc
	s_waitcnt lgkmcnt(3)
	v_mfma_f32_16x16x32_bf16 v[28:31], v[32:35], v[132:135], 0
	v_cmp_le_u32_e32 vcc, v22, v18
	s_nop 1
	v_cndmask_b32_e32 v52, v217, v52, vcc
	v_cmp_le_u32_e32 vcc, v21, v18
	s_waitcnt lgkmcnt(2)
	v_mfma_f32_16x16x32_bf16 v[28:31], v[36:39], v[136:139], v[28:31]
	v_add_u32_e32 v37, 32, v25
	v_cndmask_b32_e32 v53, v217, v53, vcc
	v_cmp_le_u32_e32 vcc, v20, v18
	s_waitcnt lgkmcnt(1)
	v_mfma_f32_16x16x32_bf16 v[32:35], v[40:43], v[132:135], 0
	v_cndmask_b32_e32 v54, v217, v54, vcc
	v_cmp_le_u32_e32 vcc, v19, v18
	s_waitcnt lgkmcnt(0)
	v_mfma_f32_16x16x32_bf16 v[32:35], v[44:47], v[136:139], v[32:35]
	v_cndmask_b32_e32 v36, v217, v55, vcc
	v_cmp_le_u32_e32 vcc, v37, v18
	v_add_u32_e32 v37, 33, v25
	s_nop 0
	v_cndmask_b32_e32 v28, v217, v28, vcc
	v_cmp_le_u32_e32 vcc, v37, v18
	v_add_u32_e32 v37, 34, v25
	s_nop 0
	v_cndmask_b32_e32 v29, v217, v29, vcc
	v_cmp_le_u32_e32 vcc, v37, v18
	v_add_u32_e32 v37, 35, v25
	s_nop 0
	v_cndmask_b32_e32 v30, v217, v30, vcc
	v_cmp_le_u32_e32 vcc, v37, v18
	v_add_u32_e32 v37, 36, v25
	s_nop 0
	v_cndmask_b32_e32 v31, v217, v31, vcc
	v_cmp_le_u32_e32 vcc, v37, v18
	v_add_u32_e32 v37, 37, v25
	s_nop 0
	v_cndmask_b32_e32 v32, v217, v32, vcc
	v_cmp_le_u32_e32 vcc, v37, v18
	v_add_u32_e32 v37, 38, v25
	s_nop 0
	v_cndmask_b32_e32 v33, v217, v33, vcc
	v_cmp_le_u32_e32 vcc, v37, v18
	v_add_u32_e32 v37, 39, v25
	s_nop 0
	v_cndmask_b32_e32 v34, v217, v34, vcc
	v_cmp_le_u32_e32 vcc, v37, v18
	v_max3_f32 v37, v27, s62, v64
	v_max3_f32 v37, v37, v65, v66
	v_max3_f32 v37, v37, v52, v53
	v_max3_f32 v37, v37, v54, v36
	v_max3_f32 v37, v37, v28, v29
	v_max3_f32 v37, v37, v30, v31
	v_cndmask_b32_e32 v35, v217, v35, vcc
	v_max3_f32 v37, v37, v32, v33
	v_max3_f32 v37, v37, v34, v35
	ds_bpermute_b32 v38, v0, v37
	s_waitcnt lgkmcnt(0)
	v_max_f32_e32 v38, v38, v38
	v_max_f32_e32 v37, v37, v38
	ds_bpermute_b32 v38, v222, v37
	s_waitcnt lgkmcnt(0)
	v_max3_f32 v226, v223, v37, v38
	v_sub_f32_e32 v27, v27, v226
	v_exp_f32_e32 v27, v27
	v_sub_f32_e32 v38, v64, v226
	v_exp_f32_e32 v38, v38
	v_sub_f32_e32 v39, v65, v226
	v_sub_f32_e32 v28, v28, v226
	v_exp_f32_e32 v39, v39
	v_sub_f32_e32 v40, v66, v226
	v_exp_f32_e32 v90, v28
	v_sub_f32_e32 v28, v29, v226
	v_exp_f32_e32 v40, v40
	v_sub_f32_e32 v42, v52, v226
	v_exp_f32_e32 v91, v28
	v_sub_f32_e32 v28, v30, v226
	v_add_f32_e32 v41, 0, v27
	v_exp_f32_e32 v42, v42
	v_sub_f32_e32 v43, v53, v226
	v_exp_f32_e32 v156, v28
	v_sub_f32_e32 v28, v31, v226
	v_add_f32_e32 v41, v38, v41
	v_exp_f32_e32 v43, v43
	v_sub_f32_e32 v44, v54, v226
	v_exp_f32_e32 v160, v28
	v_sub_f32_e32 v28, v32, v226
	v_add_f32_e32 v41, v39, v41
	v_exp_f32_e32 v44, v44
	v_sub_f32_e32 v36, v36, v226
	v_exp_f32_e32 v161, v28
	v_sub_f32_e32 v28, v33, v226
	v_sub_f32_e32 v37, v223, v226
	v_add_f32_e32 v41, v40, v41
	v_exp_f32_e32 v36, v36
	v_exp_f32_e32 v162, v28
	v_sub_f32_e32 v28, v34, v226
	v_add_f32_e32 v41, v42, v41
	v_exp_f32_e32 v164, v28
	v_sub_f32_e32 v64, v35, v226
	v_exp_f32_e32 v88, v37
	v_cvt_pk_bf16_f32 v28, v27, v38
	v_cvt_pk_bf16_f32 v29, v39, v40
	v_cvt_pk_bf16_f32 v30, v42, v43
	v_cvt_pk_bf16_f32 v31, v44, v36
	ds_read_b64_tr_b16 v[34:35], v225 offset:576
	ds_read_b64_tr_b16 v[32:33], v225
	v_add_f32_e32 v41, v43, v41
	v_add_f32_e32 v41, v44, v41
	v_add_f32_e32 v89, v36, v41
	ds_read_b64_tr_b16 v[42:43], v225 offset:608
	ds_read_b64_tr_b16 v[40:41], v225 offset:32
	ds_read_b64_tr_b16 v[44:45], v225 offset:64
	ds_read_b64_tr_b16 v[52:53], v225 offset:96
	ds_read_b64_tr_b16 v[46:47], v225 offset:640
	ds_read_b64_tr_b16 v[54:55], v225 offset:672
	v_pk_mul_f32 v[38:39], v[154:155], v[88:89] op_sel_hi:[1,0]
	v_pk_mul_f32 v[36:37], v[152:153], v[88:89] op_sel_hi:[1,0]
	v_exp_f32_e32 v27, v64
	v_pk_mul_f32 v[66:67], v[142:143], v[88:89] op_sel_hi:[1,0]
	s_waitcnt lgkmcnt(6)
	v_mfma_f32_16x16x32_bf16 v[32:35], v[32:35], v[28:31], v[36:39]
	v_mul_f32_e64 v64, v140, v88
	v_mul_f32_e64 v65, v141, v88
	s_nop 0
	v_pk_mul_f32 v[38:39], v[150:151], v[88:89] op_sel_hi:[1,0]
	v_pk_mul_f32 v[36:37], v[148:149], v[88:89] op_sel_hi:[1,0]
	s_waitcnt lgkmcnt(4)
	s_nop 0
	v_mfma_f32_16x16x32_bf16 v[36:39], v[40:43], v[28:31], v[36:39]
	v_mul_f32_e64 v42, v146, v88
	v_mul_f32_e64 v43, v147, v88
	v_pk_mul_f32 v[40:41], v[144:145], v[88:89] op_sel_hi:[1,0]
	s_waitcnt lgkmcnt(1)
	s_nop 0
	v_mfma_f32_16x16x32_bf16 v[40:43], v[44:47], v[28:31], v[40:43]
	v_cvt_pk_bf16_f32 v44, v90, v91
	v_cvt_pk_bf16_f32 v45, v156, v160
	v_cvt_pk_bf16_f32 v46, v161, v162
	v_cvt_pk_bf16_f32 v47, v164, v27
	ds_read_b64_tr_b16 v[70:71], v225 offset:5184
	ds_read_b64_tr_b16 v[68:69], v225 offset:4608
	s_waitcnt lgkmcnt(0)
	v_mfma_f32_16x16x32_bf16 v[168:171], v[68:71], v[44:47], v[32:35]
	s_nop 2
	v_add_f32_e32 v32, v90, v89
	v_add_f32_e32 v32, v91, v32
	v_add_f32_e32 v32, v156, v32
	v_mfma_f32_16x16x32_bf16 v[28:31], v[52:55], v[28:31], v[64:67]
	ds_read_b64_tr_b16 v[54:55], v225 offset:5216
	ds_read_b64_tr_b16 v[52:53], v225 offset:4640
	s_nop 0
	ds_read_b64_tr_b16 v[64:65], v225 offset:4672
	ds_read_b64_tr_b16 v[76:77], v225 offset:4704
	ds_read_b64_tr_b16 v[66:67], v225 offset:5248
	ds_read_b64_tr_b16 v[78:79], v225 offset:5280
	v_add_f32_e32 v32, v160, v32
	v_add_f32_e32 v32, v161, v32
	v_add_f32_e32 v32, v162, v32
	s_waitcnt lgkmcnt(0)
	v_add_f32_e32 v32, v164, v32
	v_add_f32_e32 v227, v27, v32
	s_waitcnt lgkmcnt(4)
	v_mfma_f32_16x16x32_bf16 v[156:159], v[52:55], v[44:47], v[36:39]
	v_fmac_f32_e32 v227, v224, v88
	s_waitcnt lgkmcnt(1)
	v_mfma_f32_16x16x32_bf16 v[160:163], v[64:67], v[44:47], v[40:43]
	s_waitcnt lgkmcnt(0)
	v_mfma_f32_16x16x32_bf16 v[164:167], v[76:79], v[44:47], v[28:31]

.LBB0_550:
	s_setprio 0
	s_cmp_lt_i32 s67, 2
	s_cselect_b64 s[18:19], -1, 0
	s_cmp_lt_i32 s77, 2
	s_cselect_b64 s[38:39], -1, 0
	s_or_b64 s[16:17], s[18:19], s[38:39]
	s_mov_b64 s[0:1], -1
	v_readfirstlane_b32 s81, v0
	v_readfirstlane_b32 s82, v0
	v_readfirstlane_b32 s79, v0
	s_andn2_b64 vcc, exec, s[16:17]
	v_readfirstlane_b32 s80, v0
	s_cbranch_vccnz .LBB0_544
	s_cmp_eq_u32 s75, 1
	s_cselect_b32 s0, 2, 4
	s_lshr_b32 s16, s8, s0
	s_lshl_b32 s17, s76, 6
	s_lshr_b32 s1, 0x800, s0
	s_add_i32 s16, s16, s17
	s_add_i32 s1, s1, -1
	v_add_u32_e32 v68, s16, v191
	s_waitcnt lgkmcnt(0)
	v_min_i32_e32 v2, s1, v68
	v_cmp_lt_i32_e32 vcc, -1, v68
	s_lshl_b32 s20, -1, s0
	s_andn2_b32 s20, s8, s20
	v_cndmask_b32_e32 v2, 0, v2, vcc
	v_lshlrev_b32_e32 v2, s0, v2
	v_add_u32_e32 v2, s20, v2
	v_lshl_or_b32 v2, v2, 6, v180
	v_ashrrev_i32_e32 v3, 31, v2
	v_lshlrev_b64 v[2:3], 1, v[2:3]
	v_lshl_add_u64 v[4:5], s[10:11], 0, v[2:3]
	v_lshl_add_u64 v[2:3], s[12:13], 0, v[2:3]
	global_load_dwordx4 v[4:7], v[4:5], off
	s_nop 0
	global_load_dwordx4 v[12:15], v[2:3], off
	v_add_u32_e32 v2, 8, v68
	v_min_i32_e32 v3, s1, v2
	v_cmp_lt_i32_e32 vcc, -1, v2
	s_mov_b64 s[16:17], 0
	s_nop 0
	v_cndmask_b32_e32 v2, 0, v3, vcc
	v_lshlrev_b32_e32 v2, s0, v2
	v_add_u32_e32 v2, s20, v2
	v_lshl_or_b32 v2, v2, 6, v180
	v_ashrrev_i32_e32 v3, 31, v2
	v_lshlrev_b64 v[2:3], 1, v[2:3]
	v_lshl_add_u64 v[8:9], s[10:11], 0, v[2:3]
	v_lshl_add_u64 v[2:3], s[12:13], 0, v[2:3]
	global_load_dwordx4 v[8:11], v[8:9], off
	s_nop 0
	global_load_dwordx4 v[24:27], v[2:3], off
	v_add_u32_e32 v2, 16, v68
	v_min_i32_e32 v3, s1, v2
	v_cmp_lt_i32_e32 vcc, -1, v2
	s_nop 1
	v_cndmask_b32_e32 v2, 0, v3, vcc
	v_lshlrev_b32_e32 v2, s0, v2
	v_add_u32_e32 v2, s20, v2
	v_lshl_or_b32 v2, v2, 6, v180
	v_ashrrev_i32_e32 v3, 31, v2
	v_lshlrev_b64 v[2:3], 1, v[2:3]
	v_lshl_add_u64 v[16:17], s[10:11], 0, v[2:3]
	v_lshl_add_u64 v[2:3], s[12:13], 0, v[2:3]
	global_load_dwordx4 v[16:19], v[16:17], off
	s_nop 0
	global_load_dwordx4 v[32:35], v[2:3], off
	v_add_u32_e32 v2, 24, v68
	v_min_i32_e32 v3, s1, v2
	v_cmp_lt_i32_e32 vcc, -1, v2
	s_nop 1
	v_cndmask_b32_e32 v2, 0, v3, vcc
	v_lshlrev_b32_e32 v2, s0, v2
	v_add_u32_e32 v2, s20, v2
	v_lshl_or_b32 v2, v2, 6, v180
	v_ashrrev_i32_e32 v3, 31, v2
	v_lshlrev_b64 v[2:3], 1, v[2:3]
	v_lshl_add_u64 v[20:21], s[10:11], 0, v[2:3]
	v_lshl_add_u64 v[2:3], s[12:13], 0, v[2:3]
	global_load_dwordx4 v[20:23], v[20:21], off
	s_nop 0
	global_load_dwordx4 v[40:43], v[2:3], off
	v_add_u32_e32 v2, 32, v68
	v_min_i32_e32 v3, s1, v2
	v_cmp_lt_i32_e32 vcc, -1, v2
	s_nop 1
	v_cndmask_b32_e32 v2, 0, v3, vcc
	v_lshlrev_b32_e32 v2, s0, v2
	v_add_u32_e32 v2, s20, v2
	v_lshl_or_b32 v2, v2, 6, v180
	v_ashrrev_i32_e32 v3, 31, v2
	v_lshlrev_b64 v[2:3], 1, v[2:3]
	v_lshl_add_u64 v[28:29], s[10:11], 0, v[2:3]
	v_lshl_add_u64 v[2:3], s[12:13], 0, v[2:3]
	global_load_dwordx4 v[28:31], v[28:29], off
	s_nop 0
	global_load_dwordx4 v[52:55], v[2:3], off
	v_add_u32_e32 v2, 40, v68
	v_min_i32_e32 v3, s1, v2
	v_cmp_lt_i32_e32 vcc, -1, v2
	s_nop 1
	v_cndmask_b32_e32 v2, 0, v3, vcc
	v_lshlrev_b32_e32 v2, s0, v2
	v_add_u32_e32 v2, s20, v2
	v_lshl_or_b32 v2, v2, 6, v180
	v_ashrrev_i32_e32 v3, 31, v2
	v_lshlrev_b64 v[2:3], 1, v[2:3]
	v_lshl_add_u64 v[36:37], s[10:11], 0, v[2:3]
	v_lshl_add_u64 v[2:3], s[12:13], 0, v[2:3]
	global_load_dwordx4 v[36:39], v[36:37], off
	s_nop 0
	global_load_dwordx4 v[64:67], v[2:3], off
	v_add_u32_e32 v2, 48, v68
	v_min_i32_e32 v3, s1, v2
	v_cmp_lt_i32_e32 vcc, -1, v2
	s_nop 1
	v_cndmask_b32_e32 v2, 0, v3, vcc
	v_lshlrev_b32_e32 v2, s0, v2
	v_add_u32_e32 v2, s20, v2
	v_lshl_or_b32 v2, v2, 6, v180
	v_ashrrev_i32_e32 v3, 31, v2
	v_lshlrev_b64 v[2:3], 1, v[2:3]
	v_lshl_add_u64 v[44:45], s[10:11], 0, v[2:3]
	v_lshl_add_u64 v[2:3], s[12:13], 0, v[2:3]
	global_load_dwordx4 v[44:47], v[44:45], off
	s_nop 0
	global_load_dwordx4 v[76:79], v[2:3], off
	v_add_u32_e32 v2, 56, v68
	v_min_i32_e32 v3, s1, v2
	v_cmp_lt_i32_e32 vcc, -1, v2
	s_nop 1
	v_cndmask_b32_e32 v2, 0, v3, vcc
	v_lshlrev_b32_e32 v2, s0, v2
	v_add_u32_e32 v2, s20, v2
	v_lshl_or_b32 v2, v2, 6, v180
	v_ashrrev_i32_e32 v3, 31, v2
	v_lshlrev_b64 v[2:3], 1, v[2:3]
	v_lshl_add_u64 v[68:69], s[10:11], 0, v[2:3]
	v_lshl_add_u64 v[2:3], s[12:13], 0, v[2:3]
	global_load_dwordx4 v[68:71], v[68:69], off
	s_nop 0
	global_load_dwordx4 v[88:91], v[2:3], off
	s_andn2_b64 vcc, exec, s[14:15]
	s_cbranch_vccnz .LBB0_555
	s_add_i32 s0, s76, 1
	s_cmp_lt_i32 s76, 2
	s_mov_b64 s[16:17], -1
	s_cbranch_scc1 .LBB0_554
	s_add_i32 s1, s75, 1
	s_cmp_lt_i32 s75, 2
	s_cselect_b64 s[16:17], -1, 0
	s_and_b64 s[14:15], s[16:17], exec
	s_cselect_b32 s0, s66, s0
	s_mov_b32 s75, s1

.LBB0_555:
	s_add_i32 s67, s67, 1
	s_and_b64 s[0:1], s[38:39], exec
	s_cselect_b32 s14, s66, s67
	s_and_b64 s[0:1], s[18:19], exec
	s_cselect_b32 s78, s67, s14
	s_xor_b64 s[0:1], s[18:19], -1
	v_cndmask_b32_e64 v2, 0, 1, s[0:1]
	s_waitcnt vmcnt(32)
	ds_write_b128 v219, v[48:51]
	s_waitcnt vmcnt(30)
	ds_write_b128 v219, v[60:63] offset:1152
	s_waitcnt vmcnt(28)
	ds_write_b128 v219, v[80:83] offset:2304
	s_waitcnt vmcnt(26)
	ds_write_b128 v219, v[92:95] offset:3456
	s_waitcnt vmcnt(24)
	ds_write_b128 v219, v[100:103] offset:4608
	s_waitcnt vmcnt(22)
	ds_write_b128 v219, v[108:111] offset:5760
	s_waitcnt vmcnt(20)
	ds_write_b128 v219, v[116:119] offset:6912
	s_waitcnt vmcnt(18)
	ds_write_b128 v219, v[124:127] offset:8064
	ds_write_b128 v220, v[56:59] offset:9216
	ds_write_b128 v220, v[72:75] offset:10240
	ds_write_b128 v220, v[84:87] offset:11264
	ds_write_b128 v220, v[96:99] offset:12288
	ds_write_b128 v220, v[104:107] offset:13312
	ds_write_b128 v220, v[112:115] offset:14336
	ds_write_b128 v220, v[120:123] offset:15360
	s_setprio 1
	ds_write_b128 v220, v[128:131] offset:16384
	v_readfirstlane_b32 s0, v2
	s_add_i32 s67, s77, s0
	s_cmp_eq_u32 s67, 1
	s_cselect_b32 s0, 2, 4
	s_lshl_b32 s20, s78, 6
	s_lshr_b32 s1, 16, s0
	s_sub_i32 s18, 0x80, s20
	s_lshr_b32 s0, s8, s0
	ds_read_b128 v[60:63], v228 offset:9216
	ds_read_b128 v[72:75], v229 offset:9216
	ds_read_b128 v[56:59], v230 offset:9728
	ds_read_b128 v[48:51], v231 offset:9728
	s_sub_i32 s21, s18, s0
	v_mul_u32_u24_e32 v2, s1, v173
	v_mov_b32_e32 v3, s18
	s_cmp_lg_u32 s67, 2
	v_mad_u32_u24 v3, s1, v173, v3
	s_cselect_b64 s[0:1], -1, 0
	s_cmp_lg_u32 s78, 2
	v_subrev_u32_e32 v2, s20, v2
	s_cselect_b64 s[18:19], -1, 0
	v_max_i32_e32 v80, s21, v2
	s_or_b64 s[0:1], s[0:1], s[18:19]
	v_sub_u32_e32 v2, v3, v80
	v_sub_u32_e32 v85, v176, v80
	s_mov_b64 s[14:15], -1
	s_and_b64 vcc, exec, s[0:1]
	v_cmp_le_u32_e64 s[0:1], v85, v2
	v_add_u32_e32 v86, 1, v85
	v_add_u32_e32 v84, 2, v85
	v_add_u32_e32 v83, 3, v85
	v_add_u32_e32 v82, 4, v85
	v_add_u32_e32 v81, 5, v85
	v_add_u32_e32 v80, 6, v85
	v_add_u32_e32 v3, 7, v85
	s_cbranch_vccz .LBB0_557
	s_waitcnt vmcnt(17) lgkmcnt(3)
	v_mfma_f32_16x16x32_bf16 v[92:95], v[60:63], v[132:135], 0
	ds_read_b128 v[96:99], v228 offset:13312
	ds_read_b128 v[100:103], v229 offset:13312
	v_cmp_le_u32_e32 vcc, v86, v2
	ds_read_b128 v[104:107], v230 offset:13824
	ds_read_b128 v[108:111], v231 offset:13824
	s_waitcnt vmcnt(16) lgkmcnt(6)
	v_mfma_f32_16x16x32_bf16 v[92:95], v[72:75], v[136:139], v[92:95]
	s_mov_b64 s[14:15], 0
	s_waitcnt lgkmcnt(5)
	v_mfma_f32_16x16x32_bf16 v[112:115], v[56:59], v[132:135], 0
	s_waitcnt lgkmcnt(4)
	v_mfma_f32_16x16x32_bf16 v[112:115], v[48:51], v[136:139], v[112:115]
	s_nop 2
	v_cndmask_b32_e32 v116, v217, v93, vcc
	v_cmp_le_u32_e32 vcc, v84, v2
	v_cndmask_b32_e64 v87, v217, v92, s[0:1]
	s_nop 0
	v_cndmask_b32_e32 v117, v217, v94, vcc
	v_cmp_le_u32_e32 vcc, v83, v2
	s_nop 1
	v_cndmask_b32_e32 v118, v217, v95, vcc
	s_waitcnt lgkmcnt(3)
	v_mfma_f32_16x16x32_bf16 v[92:95], v[96:99], v[132:135], 0
	v_cmp_le_u32_e32 vcc, v82, v2
	s_nop 1
	v_cndmask_b32_e32 v112, v217, v112, vcc
	v_cmp_le_u32_e32 vcc, v81, v2
	s_waitcnt lgkmcnt(2)
	v_mfma_f32_16x16x32_bf16 v[92:95], v[100:103], v[136:139], v[92:95]
	v_add_u32_e32 v101, 32, v85
	v_cndmask_b32_e32 v113, v217, v113, vcc
	v_cmp_le_u32_e32 vcc, v80, v2
	s_waitcnt lgkmcnt(1)
	v_mfma_f32_16x16x32_bf16 v[96:99], v[104:107], v[132:135], 0
	v_cndmask_b32_e32 v114, v217, v114, vcc
	v_cmp_le_u32_e32 vcc, v3, v2
	s_waitcnt lgkmcnt(0)
	v_mfma_f32_16x16x32_bf16 v[96:99], v[108:111], v[136:139], v[96:99]
	v_cndmask_b32_e32 v100, v217, v115, vcc
	v_cmp_le_u32_e32 vcc, v101, v2
	v_add_u32_e32 v101, 33, v85
	s_nop 0
	v_cndmask_b32_e32 v92, v217, v92, vcc
	v_cmp_le_u32_e32 vcc, v101, v2
	v_add_u32_e32 v101, 34, v85
	s_nop 0
	v_cndmask_b32_e32 v93, v217, v93, vcc
	v_cmp_le_u32_e32 vcc, v101, v2
	v_add_u32_e32 v101, 35, v85
	s_nop 0
	v_cndmask_b32_e32 v94, v217, v94, vcc
	v_cmp_le_u32_e32 vcc, v101, v2
	v_add_u32_e32 v101, 36, v85
	s_nop 0
	v_cndmask_b32_e32 v95, v217, v95, vcc
	v_cmp_le_u32_e32 vcc, v101, v2
	v_add_u32_e32 v101, 37, v85
	s_nop 0
	v_cndmask_b32_e32 v96, v217, v96, vcc
	v_cmp_le_u32_e32 vcc, v101, v2
	v_add_u32_e32 v101, 38, v85
	s_nop 0
	v_cndmask_b32_e32 v97, v217, v97, vcc
	v_cmp_le_u32_e32 vcc, v101, v2
	v_add_u32_e32 v101, 39, v85
	s_nop 0
	v_cndmask_b32_e32 v98, v217, v98, vcc
	v_cmp_le_u32_e32 vcc, v101, v2
	v_max3_f32 v101, v87, s62, v116
	v_max3_f32 v101, v101, v117, v118
	v_max3_f32 v101, v101, v112, v113
	v_max3_f32 v101, v101, v114, v100
	v_max3_f32 v101, v101, v92, v93
	v_max3_f32 v101, v101, v94, v95
	v_cndmask_b32_e32 v99, v217, v99, vcc
	v_max3_f32 v101, v101, v96, v97
	v_max3_f32 v101, v101, v98, v99
	ds_bpermute_b32 v102, v0, v101
	s_waitcnt lgkmcnt(0)
	v_max_f32_e32 v102, v102, v102
	v_max_f32_e32 v101, v101, v102
	ds_bpermute_b32 v102, v222, v101
	s_waitcnt lgkmcnt(0)
	v_max3_f32 v223, v226, v101, v102
	v_sub_f32_e32 v87, v87, v223
	v_exp_f32_e32 v87, v87
	v_sub_f32_e32 v102, v116, v223
	v_exp_f32_e32 v102, v102
	v_sub_f32_e32 v103, v117, v223
	v_sub_f32_e32 v92, v92, v223
	v_exp_f32_e32 v103, v103
	v_sub_f32_e32 v104, v118, v223
	v_exp_f32_e32 v130, v92
	v_sub_f32_e32 v92, v93, v223
	v_exp_f32_e32 v104, v104
	v_sub_f32_e32 v106, v112, v223
	v_exp_f32_e32 v131, v92
	v_sub_f32_e32 v92, v94, v223
	v_add_f32_e32 v105, 0, v87
	v_exp_f32_e32 v106, v106
	v_sub_f32_e32 v107, v113, v223
	v_exp_f32_e32 v140, v92
	v_sub_f32_e32 v92, v95, v223
	v_add_f32_e32 v105, v102, v105
	v_exp_f32_e32 v107, v107
	v_sub_f32_e32 v108, v114, v223
	v_exp_f32_e32 v141, v92
	v_sub_f32_e32 v92, v96, v223
	v_add_f32_e32 v105, v103, v105
	v_exp_f32_e32 v108, v108
	v_sub_f32_e32 v100, v100, v223
	v_exp_f32_e32 v142, v92
	v_sub_f32_e32 v92, v97, v223
	v_sub_f32_e32 v101, v226, v223
	v_add_f32_e32 v105, v104, v105
	v_exp_f32_e32 v100, v100
	v_exp_f32_e32 v143, v92
	v_sub_f32_e32 v92, v98, v223
	v_add_f32_e32 v105, v106, v105
	v_exp_f32_e32 v224, v92
	v_sub_f32_e32 v116, v99, v223
	v_exp_f32_e32 v128, v101
	v_cvt_pk_bf16_f32 v92, v87, v102
	v_cvt_pk_bf16_f32 v93, v103, v104
	v_cvt_pk_bf16_f32 v94, v106, v107
	v_cvt_pk_bf16_f32 v95, v108, v100
	ds_read_b64_tr_b16 v[98:99], v225 offset:576
	ds_read_b64_tr_b16 v[96:97], v225
	v_add_f32_e32 v105, v107, v105
	v_add_f32_e32 v105, v108, v105
	v_add_f32_e32 v129, v100, v105
	ds_read_b64_tr_b16 v[106:107], v225 offset:608
	ds_read_b64_tr_b16 v[104:105], v225 offset:32
	ds_read_b64_tr_b16 v[108:109], v225 offset:64
	ds_read_b64_tr_b16 v[112:113], v225 offset:96
	ds_read_b64_tr_b16 v[110:111], v225 offset:640
	ds_read_b64_tr_b16 v[114:115], v225 offset:672
	v_pk_mul_f32 v[102:103], v[170:171], v[128:129] op_sel_hi:[1,0]
	v_pk_mul_f32 v[100:101], v[168:169], v[128:129] op_sel_hi:[1,0]
	v_exp_f32_e32 v87, v116
	v_pk_mul_f32 v[118:119], v[166:167], v[128:129] op_sel_hi:[1,0]
	s_waitcnt lgkmcnt(6)
	v_mfma_f32_16x16x32_bf16 v[96:99], v[96:99], v[92:95], v[100:103]
	v_mul_f32_e64 v116, v164, v128
	v_mul_f32_e64 v117, v165, v128
	s_nop 0
	v_pk_mul_f32 v[102:103], v[158:159], v[128:129] op_sel_hi:[1,0]
	v_pk_mul_f32 v[100:101], v[156:157], v[128:129] op_sel_hi:[1,0]
	s_waitcnt lgkmcnt(4)
	s_nop 0
	v_mfma_f32_16x16x32_bf16 v[100:103], v[104:107], v[92:95], v[100:103]
	v_mul_f32_e64 v106, v162, v128
	v_mul_f32_e64 v107, v163, v128
	v_pk_mul_f32 v[104:105], v[160:161], v[128:129] op_sel_hi:[1,0]
	s_waitcnt lgkmcnt(1)
	s_nop 0
	v_mfma_f32_16x16x32_bf16 v[104:107], v[108:111], v[92:95], v[104:107]
	v_cvt_pk_bf16_f32 v108, v130, v131
	v_cvt_pk_bf16_f32 v109, v140, v141
	v_cvt_pk_bf16_f32 v110, v142, v143
	v_cvt_pk_bf16_f32 v111, v224, v87
	ds_read_b64_tr_b16 v[122:123], v225 offset:5184
	ds_read_b64_tr_b16 v[120:121], v225 offset:4608
	s_waitcnt lgkmcnt(0)
	v_mfma_f32_16x16x32_bf16 v[152:155], v[120:123], v[108:111], v[96:99]
	s_nop 2
	v_add_f32_e32 v96, v130, v129
	v_add_f32_e32 v96, v131, v96
	v_add_f32_e32 v96, v140, v96
	v_mfma_f32_16x16x32_bf16 v[92:95], v[112:115], v[92:95], v[116:119]
	ds_read_b64_tr_b16 v[114:115], v225 offset:5216
	ds_read_b64_tr_b16 v[112:113], v225 offset:4640
	s_nop 0
	ds_read_b64_tr_b16 v[116:117], v225 offset:4672
	ds_read_b64_tr_b16 v[124:125], v225 offset:4704
	ds_read_b64_tr_b16 v[118:119], v225 offset:5248
	ds_read_b64_tr_b16 v[126:127], v225 offset:5280
	v_add_f32_e32 v96, v141, v96
	v_add_f32_e32 v96, v142, v96
	v_add_f32_e32 v96, v143, v96
	s_waitcnt lgkmcnt(0)
	v_add_f32_e32 v96, v224, v96
	v_add_f32_e32 v224, v87, v96
	s_waitcnt lgkmcnt(4)
	v_mfma_f32_16x16x32_bf16 v[148:151], v[112:115], v[108:111], v[100:103]
	v_fmac_f32_e32 v224, v227, v128
	s_waitcnt lgkmcnt(1)
	v_mfma_f32_16x16x32_bf16 v[144:147], v[116:119], v[108:111], v[104:107]
	s_waitcnt lgkmcnt(0)
	v_mfma_f32_16x16x32_bf16 v[140:143], v[124:127], v[108:111], v[92:95]

.LBB0_559:
	s_setprio 0
	s_cmp_lt_i32 s78, 2
	s_cselect_b64 s[18:19], -1, 0
	s_cmp_lt_i32 s67, 2
	s_cselect_b64 s[38:39], -1, 0
	s_or_b64 s[14:15], s[18:19], s[38:39]
	s_mov_b64 s[0:1], -1
	v_readfirstlane_b32 s81, v0
	v_readfirstlane_b32 s82, v0
	v_readfirstlane_b32 s79, v0
	s_andn2_b64 vcc, exec, s[14:15]
	v_readfirstlane_b32 s80, v0
	s_cbranch_vccnz .LBB0_545
	s_cmp_eq_u32 s75, 1
	s_cselect_b32 s0, 2, 4
	s_lshr_b32 s14, s8, s0
	s_lshl_b32 s15, s76, 6
	s_lshr_b32 s1, 0x800, s0
	s_add_i32 s14, s14, s15
	s_add_i32 s1, s1, -1
	v_add_u32_e32 v124, s14, v191
	v_min_i32_e32 v2, s1, v124
	v_cmp_lt_i32_e32 vcc, -1, v124
	s_lshl_b32 s20, -1, s0
	s_andn2_b32 s20, s8, s20
	v_cndmask_b32_e32 v2, 0, v2, vcc
	v_lshlrev_b32_e32 v2, s0, v2
	v_add_u32_e32 v2, s20, v2
	v_lshl_or_b32 v2, v2, 6, v180
	v_ashrrev_i32_e32 v3, 31, v2
	v_lshlrev_b64 v[2:3], 1, v[2:3]
	s_waitcnt lgkmcnt(0)
	v_lshl_add_u64 v[48:49], s[10:11], 0, v[2:3]
	v_lshl_add_u64 v[2:3], s[12:13], 0, v[2:3]
	global_load_dwordx4 v[56:59], v[48:49], off
	s_nop 0
	global_load_dwordx4 v[48:51], v[2:3], off
	v_add_u32_e32 v2, 8, v124
	v_min_i32_e32 v3, s1, v2
	v_cmp_lt_i32_e32 vcc, -1, v2
	s_nop 1
	v_cndmask_b32_e32 v2, 0, v3, vcc
	v_lshlrev_b32_e32 v2, s0, v2
	v_add_u32_e32 v2, s20, v2
	v_lshl_or_b32 v2, v2, 6, v180
	v_ashrrev_i32_e32 v3, 31, v2
	v_lshlrev_b64 v[2:3], 1, v[2:3]
	v_lshl_add_u64 v[60:61], s[10:11], 0, v[2:3]
	v_lshl_add_u64 v[2:3], s[12:13], 0, v[2:3]
	global_load_dwordx4 v[72:75], v[60:61], off
	s_nop 0
	global_load_dwordx4 v[60:63], v[2:3], off
	v_add_u32_e32 v2, 16, v124
	v_min_i32_e32 v3, s1, v2
	v_cmp_lt_i32_e32 vcc, -1, v2
	s_nop 1
	v_cndmask_b32_e32 v2, 0, v3, vcc
	v_lshlrev_b32_e32 v2, s0, v2
	v_add_u32_e32 v2, s20, v2
	v_lshl_or_b32 v2, v2, 6, v180
	v_ashrrev_i32_e32 v3, 31, v2
	v_lshlrev_b64 v[2:3], 1, v[2:3]
	v_lshl_add_u64 v[80:81], s[10:11], 0, v[2:3]
	v_lshl_add_u64 v[2:3], s[12:13], 0, v[2:3]
	global_load_dwordx4 v[84:87], v[80:81], off
	s_nop 0
	global_load_dwordx4 v[80:83], v[2:3], off
	v_add_u32_e32 v2, 24, v124
	v_min_i32_e32 v3, s1, v2
	v_cmp_lt_i32_e32 vcc, -1, v2
	s_nop 1
	v_cndmask_b32_e32 v2, 0, v3, vcc
	v_lshlrev_b32_e32 v2, s0, v2
	v_add_u32_e32 v2, s20, v2
	v_lshl_or_b32 v2, v2, 6, v180
	v_ashrrev_i32_e32 v3, 31, v2
	v_lshlrev_b64 v[2:3], 1, v[2:3]
	v_lshl_add_u64 v[92:93], s[10:11], 0, v[2:3]
	v_lshl_add_u64 v[2:3], s[12:13], 0, v[2:3]
	global_load_dwordx4 v[96:99], v[92:93], off
	s_nop 0
	global_load_dwordx4 v[92:95], v[2:3], off
	v_add_u32_e32 v2, 32, v124
	v_min_i32_e32 v3, s1, v2
	v_cmp_lt_i32_e32 vcc, -1, v2
	s_nop 1
	v_cndmask_b32_e32 v2, 0, v3, vcc
	v_lshlrev_b32_e32 v2, s0, v2
	v_add_u32_e32 v2, s20, v2
	v_lshl_or_b32 v2, v2, 6, v180
	v_ashrrev_i32_e32 v3, 31, v2
	v_lshlrev_b64 v[2:3], 1, v[2:3]
	v_lshl_add_u64 v[100:101], s[10:11], 0, v[2:3]
	v_lshl_add_u64 v[2:3], s[12:13], 0, v[2:3]
	global_load_dwordx4 v[104:107], v[100:101], off
	s_nop 0
	global_load_dwordx4 v[100:103], v[2:3], off
	v_add_u32_e32 v2, 40, v124
	v_min_i32_e32 v3, s1, v2
	v_cmp_lt_i32_e32 vcc, -1, v2
	s_nop 1
	v_cndmask_b32_e32 v2, 0, v3, vcc
	v_lshlrev_b32_e32 v2, s0, v2
	v_add_u32_e32 v2, s20, v2
	v_lshl_or_b32 v2, v2, 6, v180
	v_ashrrev_i32_e32 v3, 31, v2
	v_lshlrev_b64 v[2:3], 1, v[2:3]
	v_lshl_add_u64 v[108:109], s[10:11], 0, v[2:3]
	v_lshl_add_u64 v[2:3], s[12:13], 0, v[2:3]
	global_load_dwordx4 v[112:115], v[108:109], off
	s_nop 0
	global_load_dwordx4 v[108:111], v[2:3], off
	v_add_u32_e32 v2, 48, v124
	v_min_i32_e32 v3, s1, v2
	v_cmp_lt_i32_e32 vcc, -1, v2
	s_nop 1
	v_cndmask_b32_e32 v2, 0, v3, vcc
	v_lshlrev_b32_e32 v2, s0, v2
	v_add_u32_e32 v2, s20, v2
	v_lshl_or_b32 v2, v2, 6, v180
	v_ashrrev_i32_e32 v3, 31, v2
	v_lshlrev_b64 v[2:3], 1, v[2:3]
	v_lshl_add_u64 v[116:117], s[10:11], 0, v[2:3]
	v_lshl_add_u64 v[2:3], s[12:13], 0, v[2:3]
	global_load_dwordx4 v[120:123], v[116:117], off
	s_nop 0
	global_load_dwordx4 v[116:119], v[2:3], off
	v_add_u32_e32 v2, 56, v124
	v_min_i32_e32 v3, s1, v2
	v_cmp_lt_i32_e32 vcc, -1, v2
	s_nop 1
	v_cndmask_b32_e32 v2, 0, v3, vcc
	v_lshlrev_b32_e32 v2, s0, v2
	v_add_u32_e32 v2, s20, v2
	v_lshl_or_b32 v2, v2, 6, v180
	v_ashrrev_i32_e32 v3, 31, v2
	v_lshlrev_b64 v[2:3], 1, v[2:3]
	v_lshl_add_u64 v[124:125], s[10:11], 0, v[2:3]
	v_lshl_add_u64 v[2:3], s[12:13], 0, v[2:3]
	global_load_dwordx4 v[128:131], v[124:125], off
	s_nop 0
	global_load_dwordx4 v[124:127], v[2:3], off
	s_andn2_b64 vcc, exec, s[16:17]
	s_mov_b64 s[0:1], 0
	s_cbranch_vccnz .LBB0_564
	s_add_i32 s16, s76, 1
	s_cmp_lt_i32 s76, 2
	s_mov_b64 s[14:15], -1
	s_cbranch_scc1 .LBB0_563
	s_add_i32 s17, s75, 1
	s_cmp_lt_i32 s75, 2
	s_cselect_b64 s[14:15], -1, 0
	s_and_b64 s[20:21], s[14:15], exec
	s_cselect_b32 s16, s66, s16
	s_mov_b32 s75, s17
